# XCD-local barriers also skip the L2 write-back when the affinity check passes (producers and consumers share the L2)
# baseline (speedup 1.0000x reference)
; __device__ __forceinline__ unsigned xb_ld(unsigned* p)              { return __hip_atomic_load(p, __ATOMIC_RELAXED, __HIP_MEMORY_SCOPE_AGENT); }
; __device__ __forceinline__ unsigned xb_add(unsigned* p, unsigned v) { return __hip_atomic_fetch_add(p, v, __ATOMIC_RELAXED, __HIP_MEMORY_SCOPE_AGENT); }
; #define XB_SPIN(cond, bar) do { unsigned _sp = 0; while (cond) { __builtin_amdgcn_s_sleep(1); \
;     if ((++_sp & 255u) == 0u) { if (xb_ld(&(bar)[XB_TMO])) break; if (_sp > XB_SPIN_CAP) { atomicAdd(&(bar)[XB_TMO], 1u); break; } } } } while (0)
; __device__ __forceinline__ void xcd_barrier(const XcdBarrier& b) {
;     ...
;         const unsigned old = xb_add(&bar[XB_XSUB(b.x)], 1u);
;         const unsigned gen = old / nloc;
;         if (old + 1u == (gen + 1u) * nloc) {
;             __builtin_amdgcn_fence(__ATOMIC_RELEASE, "agent");
;             asm volatile("s_waitcnt vmcnt(0)" ::: "memory");
;             const unsigned og = xb_add(&bar[XB_TOP], 1u);
;             const unsigned tg = og / nx;
;             if (og + 1u == (tg + 1u) * nx) xb_add(&bar[XB_TOPGEN], 1u);
;             else XB_SPIN(xb_ld(&bar[XB_TOPGEN]) == tg, bar);
.LBB0_618:
	s_andn2_saveexec_b64 s[6:7], s[6:7]
	s_cbranch_execz .LBB0_638
	s_mov_b64 s[6:7], exec
	v_readlane_b32 s100, v252, 26
	v_readlane_b32 s101, v252, 27
	s_nop 4
	global_load_dwordx4 v[4:7], v1, s[100:101] offset:32 sc1
	global_load_dwordx4 v[8:11], v1, s[100:101] offset:48 sc1
	s_waitcnt vmcnt(0)
	v_add_u32_e32 v12, -1, v4
	v_and_b32_e32 v12, v12, v4
	v_min_u32_e32 v13, v4, v5
	v_add_u32_e32 v14, -1, v5
	v_and_or_b32 v12, v14, v5, v12
	v_min_u32_e32 v13, v13, v5
	v_add_u32_e32 v14, -1, v6
	v_and_or_b32 v12, v14, v6, v12
	v_min_u32_e32 v13, v13, v6
	v_add_u32_e32 v14, -1, v7
	v_and_or_b32 v12, v14, v7, v12
	v_min_u32_e32 v13, v13, v7
	v_add_u32_e32 v14, -1, v8
	v_and_or_b32 v12, v14, v8, v12
	v_min_u32_e32 v13, v13, v8
	v_add_u32_e32 v14, -1, v9
	v_and_or_b32 v12, v14, v9, v12
	v_min_u32_e32 v13, v13, v9
	v_add_u32_e32 v14, -1, v10
	v_and_or_b32 v12, v14, v10, v12
	v_min_u32_e32 v13, v13, v10
	v_add_u32_e32 v14, -1, v11
	v_and_or_b32 v12, v14, v11, v12
	v_min_u32_e32 v13, v13, v11
	v_cmp_eq_u32_e32 vcc, 0, v13
	s_nop 1
	v_cndmask_b32_e64 v13, 0, 1, vcc
	v_or_b32_e32 v12, v12, v13
	s_nop 0
	v_readfirstlane_b32 s98, v12
	s_cmp_eq_u32 s98, 0
	s_cbranch_scc1 .LBB0_635
	buffer_wbl2 sc1
	s_waitcnt lgkmcnt(0)
	s_waitcnt vmcnt(0)
	v_mbcnt_lo_u32_b32 v0, s6, 0
	v_mbcnt_hi_u32_b32 v0, s7, v0
	v_cmp_eq_u32_e32 vcc, 0, v0
	s_and_saveexec_b64 s[8:9], vcc
	s_cbranch_execz .LBB0_621
	s_bcnt1_i32_b64 s6, s[6:7]
	v_mov_b32_e32 v3, s6
	v_readlane_b32 s6, v252, 24
	v_readlane_b32 s7, v252, 25
	s_nop 4
	global_atomic_add v3, v1, v3, s[6:7] sc0

; __device__ __forceinline__ unsigned xb_ld(unsigned* p)              { return __hip_atomic_load(p, __ATOMIC_RELAXED, __HIP_MEMORY_SCOPE_AGENT); }
; __device__ __forceinline__ unsigned xb_add(unsigned* p, unsigned v) { return __hip_atomic_fetch_add(p, v, __ATOMIC_RELAXED, __HIP_MEMORY_SCOPE_AGENT); }
; #define XB_SPIN(cond, bar) do { unsigned _sp = 0; while (cond) { __builtin_amdgcn_s_sleep(1); \
;     if ((++_sp & 255u) == 0u) { if (xb_ld(&(bar)[XB_TMO])) break; if (_sp > XB_SPIN_CAP) { atomicAdd(&(bar)[XB_TMO], 1u); break; } } } } while (0)
; __device__ __forceinline__ void xcd_barrier(const XcdBarrier& b) {
;     ...
;         const unsigned old = xb_add(&bar[XB_XSUB(b.x)], 1u);
;         const unsigned gen = old / nloc;
;         if (old + 1u == (gen + 1u) * nloc) {
;             __builtin_amdgcn_fence(__ATOMIC_RELEASE, "agent");
;             asm volatile("s_waitcnt vmcnt(0)" ::: "memory");
;             const unsigned og = xb_add(&bar[XB_TOP], 1u);
;             const unsigned tg = og / nx;
;             if (og + 1u == (tg + 1u) * nx) xb_add(&bar[XB_TOPGEN], 1u);
;             else XB_SPIN(xb_ld(&bar[XB_TOPGEN]) == tg, bar);
.LBB0_706:
	s_andn2_saveexec_b64 s[6:7], s[6:7]
	s_cbranch_execz .LBB0_726
	s_mov_b64 s[6:7], exec
	v_readlane_b32 s100, v252, 26
	v_readlane_b32 s101, v252, 27
	s_nop 4
	global_load_dwordx4 v[4:7], v1, s[100:101] offset:32 sc1
	global_load_dwordx4 v[8:11], v1, s[100:101] offset:48 sc1
	s_waitcnt vmcnt(0)
	v_add_u32_e32 v12, -1, v4
	v_and_b32_e32 v12, v12, v4
	v_min_u32_e32 v13, v4, v5
	v_add_u32_e32 v14, -1, v5
	v_and_or_b32 v12, v14, v5, v12
	v_min_u32_e32 v13, v13, v5
	v_add_u32_e32 v14, -1, v6
	v_and_or_b32 v12, v14, v6, v12
	v_min_u32_e32 v13, v13, v6
	v_add_u32_e32 v14, -1, v7
	v_and_or_b32 v12, v14, v7, v12
	v_min_u32_e32 v13, v13, v7
	v_add_u32_e32 v14, -1, v8
	v_and_or_b32 v12, v14, v8, v12
	v_min_u32_e32 v13, v13, v8
	v_add_u32_e32 v14, -1, v9
	v_and_or_b32 v12, v14, v9, v12
	v_min_u32_e32 v13, v13, v9
	v_add_u32_e32 v14, -1, v10
	v_and_or_b32 v12, v14, v10, v12
	v_min_u32_e32 v13, v13, v10
	v_add_u32_e32 v14, -1, v11
	v_and_or_b32 v12, v14, v11, v12
	v_min_u32_e32 v13, v13, v11
	v_cmp_eq_u32_e32 vcc, 0, v13
	s_nop 1
	v_cndmask_b32_e64 v13, 0, 1, vcc
	v_or_b32_e32 v12, v12, v13
	s_nop 0
	v_readfirstlane_b32 s98, v12
	s_cmp_eq_u32 s98, 0
	s_cbranch_scc1 .LBB0_723
	buffer_wbl2 sc1
	s_waitcnt lgkmcnt(0)
	s_waitcnt vmcnt(0)
	v_mbcnt_lo_u32_b32 v0, s6, 0
	v_mbcnt_hi_u32_b32 v0, s7, v0
	v_cmp_eq_u32_e32 vcc, 0, v0
	s_and_saveexec_b64 s[14:15], vcc
	s_cbranch_execz .LBB0_709
	s_bcnt1_i32_b64 s6, s[6:7]
	v_mov_b32_e32 v3, s6
	v_readlane_b32 s6, v252, 24
	v_readlane_b32 s7, v252, 25
	s_nop 4
	global_atomic_add v3, v1, v3, s[6:7] sc0

; __device__ __forceinline__ unsigned xb_ld(unsigned* p)              { return __hip_atomic_load(p, __ATOMIC_RELAXED, __HIP_MEMORY_SCOPE_AGENT); }
; __device__ __forceinline__ unsigned xb_add(unsigned* p, unsigned v) { return __hip_atomic_fetch_add(p, v, __ATOMIC_RELAXED, __HIP_MEMORY_SCOPE_AGENT); }
; #define XB_SPIN(cond, bar) do { unsigned _sp = 0; while (cond) { __builtin_amdgcn_s_sleep(1); \
;     if ((++_sp & 255u) == 0u) { if (xb_ld(&(bar)[XB_TMO])) break; if (_sp > XB_SPIN_CAP) { atomicAdd(&(bar)[XB_TMO], 1u); break; } } } } while (0)
; __device__ __forceinline__ void xcd_barrier(const XcdBarrier& b) {
;     ...
;         const unsigned old = xb_add(&bar[XB_XSUB(b.x)], 1u);
;         const unsigned gen = old / nloc;
;         if (old + 1u == (gen + 1u) * nloc) {
;             __builtin_amdgcn_fence(__ATOMIC_RELEASE, "agent");
;             asm volatile("s_waitcnt vmcnt(0)" ::: "memory");
;             const unsigned og = xb_add(&bar[XB_TOP], 1u);
;             const unsigned tg = og / nx;
;             if (og + 1u == (tg + 1u) * nx) xb_add(&bar[XB_TOPGEN], 1u);
;             else XB_SPIN(xb_ld(&bar[XB_TOPGEN]) == tg, bar);
.LBB0_778:
	s_andn2_saveexec_b64 s[6:7], s[6:7]
	s_cbranch_execz .LBB0_798
	s_mov_b64 s[10:11], exec
	v_readlane_b32 s100, v252, 26
	v_readlane_b32 s101, v252, 27
	s_nop 4
	global_load_dwordx4 v[4:7], v1, s[100:101] offset:32 sc1
	global_load_dwordx4 v[8:11], v1, s[100:101] offset:48 sc1
	s_waitcnt vmcnt(0)
	v_add_u32_e32 v12, -1, v4
	v_and_b32_e32 v12, v12, v4
	v_min_u32_e32 v13, v4, v5
	v_add_u32_e32 v14, -1, v5
	v_and_or_b32 v12, v14, v5, v12
	v_min_u32_e32 v13, v13, v5
	v_add_u32_e32 v14, -1, v6
	v_and_or_b32 v12, v14, v6, v12
	v_min_u32_e32 v13, v13, v6
	v_add_u32_e32 v14, -1, v7
	v_and_or_b32 v12, v14, v7, v12
	v_min_u32_e32 v13, v13, v7
	v_add_u32_e32 v14, -1, v8
	v_and_or_b32 v12, v14, v8, v12
	v_min_u32_e32 v13, v13, v8
	v_add_u32_e32 v14, -1, v9
	v_and_or_b32 v12, v14, v9, v12
	v_min_u32_e32 v13, v13, v9
	v_add_u32_e32 v14, -1, v10
	v_and_or_b32 v12, v14, v10, v12
	v_min_u32_e32 v13, v13, v10
	v_add_u32_e32 v14, -1, v11
	v_and_or_b32 v12, v14, v11, v12
	v_min_u32_e32 v13, v13, v11
	v_cmp_eq_u32_e32 vcc, 0, v13
	s_nop 1
	v_cndmask_b32_e64 v13, 0, 1, vcc
	v_or_b32_e32 v12, v12, v13
	s_nop 0
	v_readfirstlane_b32 s98, v12
	s_cmp_eq_u32 s98, 0
	s_cbranch_scc1 .LBB0_795
	buffer_wbl2 sc1
	s_waitcnt lgkmcnt(0)
	s_waitcnt vmcnt(0)
	v_mbcnt_lo_u32_b32 v0, s10, 0
	v_mbcnt_hi_u32_b32 v0, s11, v0
	v_cmp_eq_u32_e32 vcc, 0, v0
	s_and_saveexec_b64 s[12:13], vcc
	s_cbranch_execz .LBB0_781
	s_bcnt1_i32_b64 s10, s[10:11]
	v_mov_b32_e32 v3, s10
	v_readlane_b32 s10, v252, 24
	v_readlane_b32 s11, v252, 25
	s_nop 4
	global_atomic_add v3, v1, v3, s[10:11] sc0
